# Same as the v34 kernel plus two wait states before each register move that replaces a load in the attention unit epilogue
# speedup vs baseline: 1.0236x; 1.0047x over previous
; #define LAS __attribute__((address_space(3)))
; #define LAS __attribute__((address_space(3)))
; DI void attn_unit(const bf16_t* z, const bf16_t* VT, bf16_t* Y, const float* subg, ldsp lds, int tid, int b, int h, int qb, float lam, float ns, float oscale, int win) {
;     ...
;     __syncthreads();
;     if (!comp) {
;         float ss0 = 0.f, ss1 = 0.f;
; #pragma unroll
;         for (int e = 0; e < 8; ++e)
; #pragma unroll
;             for (int qt = 0; qt < 2; ++qt)
; #pragma unroll
;                 for (int r = 0; r < 4; ++r) {
;                     const float o = O[e][qt][r] * (qt ? sc1 : sc0) - *(LAS float*)(xp + ((2 * e + qt) * 4 + r) * 256);
;                     O[e][qt][r] = o; if (qt) ss1 += o * o; else ss0 += o * o;
;                 }
.LBB0_421:
	s_andn2_b64 vcc, exec, s[0:1]
	s_waitcnt lgkmcnt(0)
	s_barrier
	s_cbranch_vccnz .LBB0_401
	ds_read2st64_b32 v[60:61], v70 offset1:1
	ds_read2st64_b32 v[62:63], v70 offset0:4 offset1:5
	ds_read2st64_b32 v[64:65], v70 offset0:6 offset1:7
	ds_read2st64_b32 v[66:67], v70 offset0:2 offset1:3
	v_mov_b32_e32 v59, v72
	s_waitcnt lgkmcnt(3)
	v_mov_b32_e32 v69, v60
	v_mov_b32_e32 v72, v77
	s_waitcnt lgkmcnt(2)
	v_mov_b32_e32 v60, v63
	v_mov_b32_e32 v58, v76
	v_mov_b32_e32 v68, v62
	v_pk_fma_f32 v[60:61], v[72:73], v[56:57], v[60:61] neg_lo:[0,0,1] neg_hi:[0,0,1]
	v_pk_fma_f32 v[58:59], v[58:59], v[56:57], v[68:69] neg_lo:[0,0,1] neg_hi:[0,0,1]
	v_pk_mul_f32 v[62:63], v[60:61], v[60:61]
	s_waitcnt lgkmcnt(1)
	v_mov_b32_e32 v72, v64
	v_pk_fma_f32 v[68:69], v[58:59], v[58:59], v[62:63]
	v_mov_b32_e32 v62, v78
	v_mov_b32_e32 v63, v74
	s_waitcnt lgkmcnt(0)
	v_mov_b32_e32 v73, v66
	v_mov_b32_e32 v74, v79
	v_mov_b32_e32 v66, v65
	v_pk_fma_f32 v[62:63], v[62:63], v[56:57], v[72:73] neg_lo:[0,0,1] neg_hi:[0,0,1]
	v_pk_fma_f32 v[64:65], v[74:75], v[56:57], v[66:67] neg_lo:[0,0,1] neg_hi:[0,0,1]
	ds_read2st64_b32 v[72:73], v70 offset0:8 offset1:9
	ds_read2st64_b32 v[74:75], v70 offset0:12 offset1:13
	ds_read2st64_b32 v[76:77], v70 offset0:14 offset1:15
	ds_read2st64_b32 v[78:79], v70 offset0:10 offset1:11
	v_pk_fma_f32 v[68:69], v[62:63], v[62:63], v[68:69]
	v_mov_b32_e32 v66, v48
	v_mov_b32_e32 v67, v52
	s_waitcnt lgkmcnt(2)
	v_mov_b32_e32 v80, v74
	v_mov_b32_e32 v81, v72
	v_pk_fma_f32 v[66:67], v[66:67], v[56:57], v[80:81] neg_lo:[0,0,1] neg_hi:[0,0,1]
	v_mov_b32_e32 v52, v49
	v_pk_fma_f32 v[48:49], v[64:65], v[64:65], v[68:69]
	v_mov_b32_e32 v72, v75
	ds_read2st64_b32 v[80:81], v70 offset0:16 offset1:17
	ds_read2st64_b32 v[82:83], v70 offset0:18 offset1:19
	ds_read2st64_b32 v[84:85], v70 offset0:20 offset1:21
	ds_read2st64_b32 v[86:87], v70 offset0:22 offset1:23
	ds_read2st64_b32 v[88:89], v70 offset0:24 offset1:25
	ds_read2st64_b32 v[90:91], v70 offset0:28 offset1:29
	v_pk_fma_f32 v[68:69], v[66:67], v[66:67], v[48:49]
	v_pk_fma_f32 v[48:49], v[52:53], v[56:57], v[72:73] neg_lo:[0,0,1] neg_hi:[0,0,1]
	v_mov_b32_e32 v52, v50
	v_mov_b32_e32 v53, v54
	s_waitcnt lgkmcnt(7)
	v_mov_b32_e32 v72, v76
	s_waitcnt lgkmcnt(6)
	v_mov_b32_e32 v73, v78
	v_pk_fma_f32 v[68:69], v[48:49], v[48:49], v[68:69]
	v_pk_fma_f32 v[52:53], v[52:53], v[56:57], v[72:73] neg_lo:[0,0,1] neg_hi:[0,0,1]
	v_mov_b32_e32 v54, v51
	v_mov_b32_e32 v78, v77
	v_pk_fma_f32 v[68:69], v[52:53], v[52:53], v[68:69]
	v_pk_fma_f32 v[54:55], v[54:55], v[56:57], v[78:79] neg_lo:[0,0,1] neg_hi:[0,0,1]
	v_mov_b32_e32 v50, v40
	v_mov_b32_e32 v51, v44
	s_waitcnt lgkmcnt(3)
	v_mov_b32_e32 v72, v84
	v_mov_b32_e32 v73, v80
	v_mov_b32_e32 v44, v41
	v_mov_b32_e32 v80, v85
	v_pk_fma_f32 v[68:69], v[54:55], v[54:55], v[68:69]
	v_pk_fma_f32 v[50:51], v[50:51], v[56:57], v[72:73] neg_lo:[0,0,1] neg_hi:[0,0,1]
	v_pk_fma_f32 v[40:41], v[44:45], v[56:57], v[80:81] neg_lo:[0,0,1] neg_hi:[0,0,1]
	v_mov_b32_e32 v44, v42
	v_mov_b32_e32 v45, v46
	s_waitcnt lgkmcnt(2)
	v_mov_b32_e32 v72, v86
	v_mov_b32_e32 v73, v82
	v_pk_fma_f32 v[68:69], v[50:51], v[50:51], v[68:69]
	v_pk_fma_f32 v[44:45], v[44:45], v[56:57], v[72:73] neg_lo:[0,0,1] neg_hi:[0,0,1]
	ds_read2st64_b32 v[72:73], v70 offset0:30 offset1:31
	ds_read2st64_b32 v[74:75], v70 offset0:26 offset1:27
	v_pk_fma_f32 v[68:69], v[40:41], v[40:41], v[68:69]
	v_mov_b32_e32 v46, v43
	v_mov_b32_e32 v82, v87
	v_pk_fma_f32 v[68:69], v[44:45], v[44:45], v[68:69]
	v_pk_fma_f32 v[42:43], v[46:47], v[56:57], v[82:83] neg_lo:[0,0,1] neg_hi:[0,0,1]
	v_mov_b32_e32 v46, v32
	v_mov_b32_e32 v47, v36
	s_waitcnt lgkmcnt(2)
	v_mov_b32_e32 v76, v90
	v_mov_b32_e32 v77, v88
	v_pk_fma_f32 v[68:69], v[42:43], v[42:43], v[68:69]
	v_pk_fma_f32 v[46:47], v[46:47], v[56:57], v[76:77] neg_lo:[0,0,1] neg_hi:[0,0,1]
	v_mov_b32_e32 v36, v33
	v_mov_b32_e32 v88, v91
	v_pk_fma_f32 v[68:69], v[46:47], v[46:47], v[68:69]
	v_pk_fma_f32 v[32:33], v[36:37], v[56:57], v[88:89] neg_lo:[0,0,1] neg_hi:[0,0,1]
	v_mov_b32_e32 v37, v38
	v_pk_fma_f32 v[76:77], v[32:33], v[32:33], v[68:69]
	s_waitcnt lgkmcnt(0)
	v_mov_b32_e32 v69, v74
	v_mov_b32_e32 v38, v35
	v_mov_b32_e32 v74, v73
	v_mov_b32_e32 v36, v34
	v_mov_b32_e32 v68, v72
	v_pk_fma_f32 v[34:35], v[38:39], v[56:57], v[74:75] neg_lo:[0,0,1] neg_hi:[0,0,1]
	ds_read2st64_b32 v[74:75], v70 offset0:32 offset1:33
	ds_read2st64_b32 v[78:79], v70 offset0:34 offset1:35
	ds_read2st64_b32 v[80:81], v70 offset0:36 offset1:37
	ds_read2st64_b32 v[82:83], v70 offset0:38 offset1:39
	ds_read2st64_b32 v[38:39], v70 offset0:48 offset1:49
	ds_read2st64_b32 v[84:85], v70 offset0:40 offset1:41
	ds_read2st64_b32 v[86:87], v70 offset0:42 offset1:43
	ds_read2st64_b32 v[88:89], v70 offset0:44 offset1:45
	ds_read2st64_b32 v[90:91], v70 offset0:46 offset1:47
	ds_read2st64_b32 v[92:93], v70 offset0:50 offset1:51
	ds_read2st64_b32 v[94:95], v70 offset0:52 offset1:53
	ds_read2st64_b32 v[96:97], v70 offset0:54 offset1:55
	v_pk_fma_f32 v[36:37], v[36:37], v[56:57], v[68:69] neg_lo:[0,0,1] neg_hi:[0,0,1]
	s_waitcnt lgkmcnt(7)
	v_pk_fma_f32 v[68:69], v[24:25], v[56:57], v[38:39] op_sel:[0,1,0] neg_lo:[0,0,1] neg_hi:[0,0,1]
	v_pk_fma_f32 v[24:25], v[36:37], v[36:37], v[76:77]
	v_mov_b32_e32 v72, v20
	v_mov_b32_e32 v73, v28
	s_waitcnt lgkmcnt(2)
; #define LAS __attribute__((address_space(3)))
; #define LAS __attribute__((address_space(3)))
; DI unsigned pk(float lo, float hi) { return pg8::cvt_pk_bf16(lo, hi); }
; DI void attn_unit(const bf16_t* z, const bf16_t* VT, bf16_t* Y, const float* subg, ldsp lds, int tid, int b, int h, int qb, float lam, float ns, float oscale, int win) {
;     ...
;                 for (int r = 0; r < 4; ++r) {
;                     const float o = O[e][qt][r] * (qt ? sc1 : sc0) - *(LAS float*)(xp + ((2 * e + qt) * 4 + r) * 256);
;                     O[e][qt][r] = o; if (qt) ss1 += o * o; else ss0 += o * o;
;                 }
;         ss0 += __shfl_xor(ss0, 16); ss0 += __shfl_xor(ss0, 32);
;         ss1 += __shfl_xor(ss1, 16); ss1 += __shfl_xor(ss1, 32);
;         const float r0 = rsqrtf(ss0 * (1.0f / 128.0f) + EPS) * oscale, r1 = rsqrtf(ss1 * (1.0f / 128.0f) + EPS) * oscale;
; #pragma unroll
;         for (int qt = 0; qt < 2; ++qt) {
;             bf16_t* yrow = Y + (size_t)(b * SEQ + q0 + 16 * qt + fr) * D + 256 + h * 128;
;             const float rr = qt ? r1 : r0;
; #pragma unroll
;             for (int e = 0; e < 8; ++e) {
;                 const int e0 = 16 * e + 4 * fq;
;                 const f32x4 gn = *(const f32x4*)(subg + e0);
;                 u32x2 o; o.x = pk(O[e][qt][0] * rr * gn[0], O[e][qt][1] * rr * gn[1]); o.y = pk(O[e][qt][2] * rr * gn[2], O[e][qt][3] * rr * gn[3]);
;                 *(u32x2*)(yrow + e0) = o;
	v_pk_fma_f32 v[38:39], v[26:27], v[56:57], v[92:93] op_sel:[0,1,0] neg_lo:[0,0,1] neg_hi:[0,0,1]
	v_pk_fma_f32 v[26:27], v[34:35], v[34:35], v[24:25]
	v_mov_b32_e32 v24, v80
	v_mov_b32_e32 v25, v74
	v_pk_fma_f32 v[24:25], v[72:73], v[56:57], v[24:25] neg_lo:[0,0,1] neg_hi:[0,0,1]
	v_mov_b32_e32 v28, v21
	v_mov_b32_e32 v74, v81
	v_pk_fma_f32 v[26:27], v[24:25], v[24:25], v[26:27]
	v_pk_fma_f32 v[20:21], v[28:29], v[56:57], v[74:75] neg_lo:[0,0,1] neg_hi:[0,0,1]
	v_mov_b32_e32 v72, v82
	v_pk_fma_f32 v[28:29], v[20:21], v[20:21], v[26:27]
	v_mov_b32_e32 v26, v22
	v_mov_b32_e32 v27, v30
	v_mov_b32_e32 v73, v78
	v_pk_fma_f32 v[26:27], v[26:27], v[56:57], v[72:73] neg_lo:[0,0,1] neg_hi:[0,0,1]
	v_mov_b32_e32 v30, v23
	v_mov_b32_e32 v78, v83
	v_pk_fma_f32 v[72:73], v[26:27], v[26:27], v[28:29]
	v_pk_fma_f32 v[28:29], v[30:31], v[56:57], v[78:79] neg_lo:[0,0,1] neg_hi:[0,0,1]
	v_mov_b32_e32 v22, v12
	v_pk_fma_f32 v[30:31], v[28:29], v[28:29], v[72:73]
	v_mov_b32_e32 v23, v16
	v_mov_b32_e32 v72, v88
	v_mov_b32_e32 v73, v84
	v_lshlrev_b32_e32 v88, 4, v177
	v_pk_fma_f32 v[22:23], v[22:23], v[56:57], v[72:73] neg_lo:[0,0,1] neg_hi:[0,0,1]
	global_load_dwordx4 v[72:75], v88, s[26:27]
	global_load_dwordx4 v[142:145], v88, s[26:27]
	global_load_dwordx4 v[100:103], v88, s[26:27] offset:64
	global_load_dwordx4 v[104:107], v88, s[26:27] offset:128
	global_load_dwordx4 v[108:111], v88, s[26:27] offset:192
	global_load_dwordx4 v[112:115], v88, s[26:27] offset:256
	global_load_dwordx4 v[130:133], v88, s[26:27] offset:320
	global_load_dwordx4 v[146:149], v88, s[26:27] offset:384
	global_load_dwordx4 v[150:153], v88, s[26:27] offset:448
	v_mov_b32_e32 v16, v13
	v_mov_b32_e32 v84, v89
	v_pk_fma_f32 v[30:31], v[22:23], v[22:23], v[30:31]
	v_pk_fma_f32 v[12:13], v[16:17], v[56:57], v[84:85] neg_lo:[0,0,1] neg_hi:[0,0,1]
	v_mov_b32_e32 v16, v14
	v_mov_b32_e32 v17, v18
	v_mov_b32_e32 v76, v90
	v_mov_b32_e32 v77, v86
	s_waitcnt lgkmcnt(1)
	v_pk_fma_f32 v[8:9], v[8:9], v[56:57], v[94:95] op_sel_hi:[1,0,1] neg_lo:[0,0,1] neg_hi:[0,0,1]
	v_pk_fma_f32 v[30:31], v[12:13], v[12:13], v[30:31]
	v_pk_fma_f32 v[16:17], v[16:17], v[56:57], v[76:77] neg_lo:[0,0,1] neg_hi:[0,0,1]
	v_mov_b32_e32 v18, v15
	v_mov_b32_e32 v86, v91
	v_pk_mul_f32 v[98:99], v[68:69], v[68:69]
	v_pk_mul_f32 v[94:95], v[8:9], v[8:9]
	v_pk_fma_f32 v[30:31], v[16:17], v[16:17], v[30:31]
	v_pk_fma_f32 v[14:15], v[18:19], v[56:57], v[86:87] neg_lo:[0,0,1] neg_hi:[0,0,1]
	s_waitcnt lgkmcnt(0)
	v_pk_fma_f32 v[10:11], v[10:11], v[56:57], v[96:97] op_sel_hi:[1,0,1] neg_lo:[0,0,1] neg_hi:[0,0,1]
	v_pk_fma_f32 v[18:19], v[14:15], v[14:15], v[30:31]
	v_mov_b32_e32 v30, v94
	v_mov_b32_e32 v31, v98
	v_pk_add_f32 v[18:19], v[18:19], v[30:31]
	ds_read2st64_b32 v[30:31], v70 offset0:56 offset1:57
	ds_read2st64_b32 v[78:79], v70 offset0:58 offset1:59
	ds_read2st64_b32 v[80:81], v70 offset0:60 offset1:61
	ds_read2st64_b32 v[70:71], v70 offset0:62 offset1:63
	v_pk_mul_f32 v[92:93], v[38:39], v[38:39]
	v_pk_mul_f32 v[76:77], v[10:11], v[10:11]
	v_mov_b32_e32 v98, v95
	s_waitcnt lgkmcnt(3)
	v_pk_fma_f32 v[30:31], v[4:5], v[56:57], v[30:31] op_sel:[0,1,0] neg_lo:[0,0,1] neg_hi:[0,0,1]
	s_waitcnt lgkmcnt(2)
	v_pk_fma_f32 v[6:7], v[6:7], v[56:57], v[78:79] op_sel:[0,1,0] neg_lo:[0,0,1] neg_hi:[0,0,1]
	s_waitcnt lgkmcnt(1)
	v_pk_fma_f32 v[4:5], v[0:1], v[56:57], v[80:81] op_sel_hi:[1,0,1] neg_lo:[0,0,1] neg_hi:[0,0,1]
	s_waitcnt lgkmcnt(0)
	v_pk_fma_f32 v[0:1], v[2:3], v[56:57], v[70:71] op_sel_hi:[1,0,1] neg_lo:[0,0,1] neg_hi:[0,0,1]
	v_pk_add_f32 v[18:19], v[18:19], v[98:99]
	v_mov_b32_e32 v56, v76
	v_mov_b32_e32 v57, v92
	v_pk_mul_f32 v[82:83], v[30:31], v[30:31]
	v_pk_mul_f32 v[80:81], v[4:5], v[4:5]
	v_pk_add_f32 v[18:19], v[18:19], v[56:57]
	v_mov_b32_e32 v92, v77
	v_pk_add_f32 v[18:19], v[18:19], v[92:93]
	v_mov_b32_e32 v56, v80
	v_mov_b32_e32 v57, v82
	v_pk_mul_f32 v[78:79], v[6:7], v[6:7]
	v_pk_mul_f32 v[2:3], v[0:1], v[0:1]
	v_pk_add_f32 v[18:19], v[18:19], v[56:57]
	v_mov_b32_e32 v82, v81
	v_pk_add_f32 v[18:19], v[18:19], v[82:83]
	v_mov_b32_e32 v56, v2
	v_mov_b32_e32 v57, v78
	v_pk_add_f32 v[18:19], v[18:19], v[56:57]
	v_mov_b32_e32 v78, v3
	v_pk_add_f32 v[2:3], v[18:19], v[78:79]
	ds_bpermute_b32 v19, v172, v3
	ds_bpermute_b32 v18, v172, v2
	s_brev_b32 s0, 60
	s_lshl_b32 s30, s6, 1
	v_lshlrev_b32_e32 v156, 3, v177
	s_waitcnt lgkmcnt(0)
	v_pk_add_f32 v[2:3], v[2:3], v[18:19]
	ds_bpermute_b32 v19, v173, v3
	ds_bpermute_b32 v18, v173, v2
	s_waitcnt lgkmcnt(0)
	v_pk_add_f32 v[2:3], v[2:3], v[18:19]
	s_nop 0
	v_pk_fma_f32 v[2:3], v[2:3], s[0:1], v[162:163] op_sel_hi:[1,0,0]
	s_nop 0
	v_mul_f32_e32 v18, 0x4b800000, v3
	v_cmp_gt_f32_e32 vcc, s47, v3
	s_nop 1
	v_cndmask_b32_e32 v3, v3, v18, vcc
	v_rsq_f32_e32 v3, v3
	s_nop 0
	v_mul_f32_e32 v18, 0x45800000, v3
	v_cndmask_b32_e32 v3, v3, v18, vcc
	v_mul_f32_e32 v3, v176, v3
	v_lshlrev_b64 v[18:19], 11, v[120:121]
	v_mul_f32_e32 v56, v59, v3
	v_mul_f32_e32 v57, v61, v3
	v_lshl_add_u64 v[18:19], s[92:93], 0, v[18:19]
	s_waitcnt vmcnt(0)
; DI unsigned pk(float lo, float hi) { return pg8::cvt_pk_bf16(lo, hi); }
; DI void attn_unit(const bf16_t* z, const bf16_t* VT, bf16_t* Y, const float* subg, ldsp lds, int tid, int b, int h, int qb, float lam, float ns, float oscale, int win) {
;     ...
;         const float r0 = rsqrtf(ss0 * (1.0f / 128.0f) + EPS) * oscale, r1 = rsqrtf(ss1 * (1.0f / 128.0f) + EPS) * oscale;
; #pragma unroll
;         for (int qt = 0; qt < 2; ++qt) {
;             bf16_t* yrow = Y + (size_t)(b * SEQ + q0 + 16 * qt + fr) * D + 256 + h * 128;
;             const float rr = qt ? r1 : r0;
; #pragma unroll
;             for (int e = 0; e < 8; ++e) {
;                 const int e0 = 16 * e + 4 * fq;
;                 const f32x4 gn = *(const f32x4*)(subg + e0);
;                 u32x2 o; o.x = pk(O[e][qt][0] * rr * gn[0], O[e][qt][1] * rr * gn[1]); o.y = pk(O[e][qt][2] * rr * gn[2], O[e][qt][3] * rr * gn[3]);
;                 *(u32x2*)(yrow + e0) = o;
;             }
	v_mul_f32_e32 v56, v72, v56
	v_mul_f32_e32 v57, v73, v57
	v_lshl_add_u64 v[18:19], v[18:19], 0, s[30:31]
	v_cvt_pk_bf16_f32 v56, v56, v57
	v_mul_f32_e32 v57, v63, v3
	v_mul_f32_e32 v57, v74, v57
	v_mul_f32_e32 v59, v65, v3
	v_lshl_add_u64 v[18:19], v[18:19], 0, v[156:157]
	v_mul_f32_e32 v59, v75, v59
	v_cvt_pk_bf16_f32 v57, v57, v59
	global_store_dwordx2 v[18:19], v[56:57], off offset:512
	s_nop 1
	v_mov_b32_e32 v70, v100
	v_mov_b32_e32 v71, v101
	v_mov_b32_e32 v72, v102
	v_mov_b32_e32 v73, v103
	v_mul_f32_e32 v56, v67, v3
	v_mul_f32_e32 v49, v49, v3
	v_mul_f32_e32 v41, v41, v3
	v_mul_f32_e32 v45, v45, v3
	v_mul_f32_e32 v43, v43, v3
	v_mul_f32_e32 v33, v33, v3
	v_mul_f32_e32 v37, v37, v3
	v_mul_f32_e32 v35, v35, v3
	v_mul_f32_e32 v25, v25, v3
	v_mul_f32_e32 v21, v21, v3
	v_mul_f32_e32 v27, v27, v3
	v_mul_f32_e32 v29, v29, v3
	v_mul_f32_e32 v13, v13, v3
	v_mul_f32_e32 v17, v17, v3
	v_mul_f32_e32 v15, v15, v3
	v_mul_f32_e32 v6, v6, v3
	v_cmp_gt_f32_e32 vcc, s47, v2
	v_mul_f32_e32 v56, v70, v56
	v_mul_f32_e32 v49, v71, v49
	v_cvt_pk_bf16_f32 v56, v56, v49
	v_mul_f32_e32 v49, v53, v3
	v_mul_f32_e32 v53, v55, v3
	v_mul_f32_e32 v49, v72, v49
	v_mul_f32_e32 v53, v73, v53
	v_cvt_pk_bf16_f32 v57, v49, v53
	global_store_dwordx2 v[18:19], v[56:57], off offset:544
	s_nop 1
	v_mov_b32_e32 v70, v104
	v_mov_b32_e32 v71, v105
	v_mov_b32_e32 v72, v106
	v_mov_b32_e32 v73, v107
	v_mul_f32_e32 v49, v51, v3
	v_mul_f32_e32 v49, v49, v70
	v_mul_f32_e32 v41, v41, v71
	v_mul_f32_e32 v45, v45, v72
	v_mul_f32_e32 v43, v43, v73
	v_cvt_pk_bf16_f32 v56, v49, v41
	v_cvt_pk_bf16_f32 v57, v45, v43
	global_store_dwordx2 v[18:19], v[56:57], off offset:576
	s_nop 1
	v_mov_b32_e32 v70, v108
	v_mov_b32_e32 v71, v109
	v_mov_b32_e32 v72, v110
	v_mov_b32_e32 v73, v111
	v_mul_f32_e32 v41, v47, v3
	v_mul_f32_e32 v41, v41, v70
	v_mul_f32_e32 v33, v33, v71
	v_mul_f32_e32 v37, v37, v72
	v_mul_f32_e32 v35, v35, v73
	v_cvt_pk_bf16_f32 v56, v41, v33
	v_cvt_pk_bf16_f32 v57, v37, v35
	global_store_dwordx2 v[18:19], v[56:57], off offset:608
	s_nop 1
	v_mov_b32_e32 v70, v112
	v_mov_b32_e32 v71, v113
	v_mov_b32_e32 v72, v114
	v_mov_b32_e32 v73, v115
	v_mul_f32_e32 v25, v25, v70
	v_mul_f32_e32 v21, v21, v71
	v_mul_f32_e32 v27, v27, v72
	v_mul_f32_e32 v29, v29, v73
	v_cvt_pk_bf16_f32 v56, v25, v21
	v_cvt_pk_bf16_f32 v57, v27, v29
	global_store_dwordx2 v[18:19], v[56:57], off offset:640
	s_nop 1
	v_mov_b32_e32 v70, v130
	v_mov_b32_e32 v71, v131
	v_mov_b32_e32 v72, v132
	v_mov_b32_e32 v73, v133
	v_mul_f32_e32 v21, v23, v3
	v_mul_f32_e32 v21, v21, v70
	v_mul_f32_e32 v13, v13, v71
	v_mul_f32_e32 v17, v17, v72
	v_mul_f32_e32 v15, v15, v73
	v_cvt_pk_bf16_f32 v56, v21, v13
	v_cvt_pk_bf16_f32 v57, v17, v15
	global_store_dwordx2 v[18:19], v[56:57], off offset:672
	s_nop 1
	v_mov_b32_e32 v70, v146
	v_mov_b32_e32 v71, v147
	v_mov_b32_e32 v72, v148
	v_mov_b32_e32 v73, v149
	v_mul_f32_e32 v13, v68, v3
	v_mul_f32_e32 v15, v69, v3
	v_mul_f32_e32 v17, v38, v3
	v_mul_f32_e32 v21, v39, v3
	v_mul_f32_e32 v13, v13, v70
	v_mul_f32_e32 v15, v15, v71
	v_mul_f32_e32 v17, v17, v72
	v_mul_f32_e32 v21, v21, v73
	v_cvt_pk_bf16_f32 v38, v13, v15
	v_cvt_pk_bf16_f32 v39, v17, v21
	global_store_dwordx2 v[18:19], v[38:39], off offset:704
	s_nop 1
	v_mov_b32_e32 v68, v150
	v_mov_b32_e32 v69, v151
	v_mov_b32_e32 v70, v152
	v_mov_b32_e32 v71, v153
	v_mul_f32_e32 v13, v30, v3
	v_mul_f32_e32 v15, v31, v3
	v_mul_f32_e32 v3, v7, v3
	v_mul_f32_e32 v7, v13, v68
	v_mul_f32_e32 v13, v15, v69
	v_mul_f32_e32 v15, v6, v70
	v_mul_f32_e32 v3, v3, v71
	v_cvt_pk_bf16_f32 v6, v7, v13
	v_cvt_pk_bf16_f32 v7, v15, v3
	global_store_dwordx2 v[18:19], v[6:7], off offset:736
	s_nop 1
	v_mov_b32_e32 v68, v142
	v_mov_b32_e32 v69, v143
	v_mov_b32_e32 v70, v144
	v_mov_b32_e32 v71, v145
	v_mul_f32_e32 v3, 0x4b800000, v2
	v_cndmask_b32_e32 v2, v2, v3, vcc
; DI unsigned pk(float lo, float hi) { return pg8::cvt_pk_bf16(lo, hi); }
; DI void attn_unit(const bf16_t* z, const bf16_t* VT, bf16_t* Y, const float* subg, ldsp lds, int tid, int b, int h, int qb, float lam, float ns, float oscale, int win) {
;     ...
;         const float r0 = rsqrtf(ss0 * (1.0f / 128.0f) + EPS) * oscale, r1 = rsqrtf(ss1 * (1.0f / 128.0f) + EPS) * oscale;
; #pragma unroll
;         for (int qt = 0; qt < 2; ++qt) {
;             bf16_t* yrow = Y + (size_t)(b * SEQ + q0 + 16 * qt + fr) * D + 256 + h * 128;
;             const float rr = qt ? r1 : r0;
; #pragma unroll
;             for (int e = 0; e < 8; ++e) {
;                 const int e0 = 16 * e + 4 * fq;
;                 const f32x4 gn = *(const f32x4*)(subg + e0);
;                 u32x2 o; o.x = pk(O[e][qt][0] * rr * gn[0], O[e][qt][1] * rr * gn[1]); o.y = pk(O[e][qt][2] * rr * gn[2], O[e][qt][3] * rr * gn[3]);
;                 *(u32x2*)(yrow + e0) = o;
;             }
	v_rsq_f32_e32 v13, v2
	v_lshlrev_b64 v[6:7], 11, v[118:119]
	v_lshl_add_u64 v[2:3], s[92:93], 0, v[6:7]
	v_lshl_add_u64 v[2:3], v[2:3], 0, s[30:31]
	v_mul_f32_e32 v6, 0x45800000, v13
	v_cndmask_b32_e32 v6, v13, v6, vcc
	v_mul_f32_e32 v17, v176, v6
	v_mul_f32_e32 v6, v58, v17
	v_mul_f32_e32 v7, v60, v17
	v_lshl_add_u64 v[2:3], v[2:3], 0, v[156:157]
	v_mul_f32_e32 v13, v62, v17
	v_mul_f32_e32 v15, v64, v17
	v_mul_f32_e32 v1, v1, v17
	v_mul_f32_e32 v4, v4, v17
	v_mul_f32_e32 v5, v5, v17
	v_mul_f32_e32 v0, v0, v17
	v_mul_f32_e32 v6, v6, v68
	v_mul_f32_e32 v7, v7, v69
	v_mul_f32_e32 v13, v13, v70
	v_mul_f32_e32 v15, v15, v71
	v_cvt_pk_bf16_f32 v6, v6, v7
	v_cvt_pk_bf16_f32 v7, v13, v15
	global_store_dwordx2 v[2:3], v[6:7], off offset:512
	s_nop 1
	v_mov_b32_e32 v56, v100
	v_mov_b32_e32 v57, v101
	v_mov_b32_e32 v58, v102
	v_mov_b32_e32 v59, v103
	v_mul_f32_e32 v6, v66, v17
	v_mul_f32_e32 v7, v48, v17
	v_mul_f32_e32 v13, v52, v17
	v_mul_f32_e32 v15, v54, v17
	v_mul_f32_e32 v6, v6, v56
	v_mul_f32_e32 v7, v7, v57
	v_mul_f32_e32 v13, v13, v58
	v_mul_f32_e32 v15, v15, v59
	v_cvt_pk_bf16_f32 v6, v6, v7
	v_cvt_pk_bf16_f32 v7, v13, v15
	global_store_dwordx2 v[2:3], v[6:7], off offset:544
	s_nop 1
	v_mov_b32_e32 v52, v104
	v_mov_b32_e32 v53, v105
	v_mov_b32_e32 v54, v106
	v_mov_b32_e32 v55, v107
	v_mul_f32_e32 v6, v50, v17
	v_mul_f32_e32 v7, v40, v17
	v_mul_f32_e32 v13, v44, v17
	v_mul_f32_e32 v15, v42, v17
	v_mul_f32_e32 v6, v6, v52
	v_mul_f32_e32 v7, v7, v53
	v_mul_f32_e32 v13, v13, v54
	v_mul_f32_e32 v15, v15, v55
	v_cvt_pk_bf16_f32 v6, v6, v7
	v_cvt_pk_bf16_f32 v7, v13, v15
	global_store_dwordx2 v[2:3], v[6:7], off offset:576
	s_nop 1
	v_mov_b32_e32 v38, v108
	v_mov_b32_e32 v39, v109
	v_mov_b32_e32 v40, v110
	v_mov_b32_e32 v41, v111
	v_mul_f32_e32 v6, v46, v17
	v_mul_f32_e32 v7, v32, v17
	v_mul_f32_e32 v13, v36, v17
	v_mul_f32_e32 v15, v34, v17
	v_mul_f32_e32 v6, v6, v38
	v_mul_f32_e32 v7, v7, v39
	v_mul_f32_e32 v13, v13, v40
	v_mul_f32_e32 v15, v15, v41
	v_cvt_pk_bf16_f32 v6, v6, v7
	v_cvt_pk_bf16_f32 v7, v13, v15
	global_store_dwordx2 v[2:3], v[6:7], off offset:608
	s_nop 1
	v_mov_b32_e32 v30, v112
	v_mov_b32_e32 v31, v113
	v_mov_b32_e32 v32, v114
	v_mov_b32_e32 v33, v115
	v_mul_f32_e32 v6, v24, v17
	v_mul_f32_e32 v7, v20, v17
	v_mul_f32_e32 v13, v26, v17
	v_mul_f32_e32 v15, v28, v17
	v_mul_f32_e32 v6, v6, v30
	v_mul_f32_e32 v7, v7, v31
	v_mul_f32_e32 v13, v13, v32
	v_mul_f32_e32 v15, v15, v33
	v_cvt_pk_bf16_f32 v6, v6, v7
	v_cvt_pk_bf16_f32 v7, v13, v15
	global_store_dwordx2 v[2:3], v[6:7], off offset:640
	s_nop 1
	v_mov_b32_e32 v18, v130
	v_mov_b32_e32 v19, v131
	v_mov_b32_e32 v20, v132
	v_mov_b32_e32 v21, v133
	v_mul_f32_e32 v6, v22, v17
	v_mul_f32_e32 v7, v12, v17
	v_mul_f32_e32 v12, v16, v17
	v_mul_f32_e32 v13, v14, v17
	v_mul_f32_e32 v6, v6, v18
	v_mul_f32_e32 v7, v7, v19
	v_mul_f32_e32 v12, v12, v20
	v_mul_f32_e32 v13, v13, v21
	v_cvt_pk_bf16_f32 v6, v6, v7
	v_cvt_pk_bf16_f32 v7, v12, v13
	global_store_dwordx2 v[2:3], v[6:7], off offset:672
	s_nop 1
	v_mov_b32_e32 v12, v146
	v_mov_b32_e32 v13, v147
	v_mov_b32_e32 v14, v148
	v_mov_b32_e32 v15, v149
	v_mul_f32_e32 v6, v8, v17
	v_mul_f32_e32 v7, v9, v17
	v_mul_f32_e32 v8, v10, v17
	v_mul_f32_e32 v9, v11, v17
	v_mul_f32_e32 v6, v6, v12
	v_mul_f32_e32 v7, v7, v13
	v_mul_f32_e32 v8, v8, v14
	v_mul_f32_e32 v9, v9, v15
	v_cvt_pk_bf16_f32 v6, v6, v7
	v_cvt_pk_bf16_f32 v7, v8, v9
	global_store_dwordx2 v[2:3], v[6:7], off offset:704
	s_nop 1
	v_mov_b32_e32 v6, v150
	v_mov_b32_e32 v7, v151
	v_mov_b32_e32 v8, v152
	v_mov_b32_e32 v9, v153
	v_mul_f32_e32 v1, v1, v9
	v_mul_f32_e32 v4, v4, v6
	v_mul_f32_e32 v5, v5, v7
	v_mul_f32_e32 v6, v0, v8
	v_cvt_pk_bf16_f32 v0, v4, v5
	v_cvt_pk_bf16_f32 v1, v6, v1
	global_store_dwordx2 v[2:3], v[0:1], off offset:736
	s_branch .LBB0_401
